# accumulator zero-init between GEMM units with 64 v_mov_b64 instead of 128 v_mov_b32 (G1, G3, G4 unit headers)
# speedup vs baseline: 1.0048x; 1.0048x over previous
.LBB0_87:
	s_ashr_i32 s89, s88, 31
	s_lshl_b64 s[10:11], s[88:89], 19
	s_add_u32 s90, s24, s10
	s_addc_u32 s91, s25, s11
	s_and_b64 s[10:11], s[2:3], exec
	s_cselect_b32 s5, s91, s7
	s_cselect_b32 s10, s90, s6
	s_ashr_i32 s87, s86, 31
	s_lshl_b64 s[26:27], s[86:87], 19
	s_add_u32 s92, s12, s26
	s_addc_u32 s93, s13, s27
	s_and_b64 s[26:27], s[2:3], exec
	s_cselect_b32 s11, s93, s9
	s_cselect_b32 s26, s92, s8
	s_add_u32 s6, s6, 0x40080
	s_addc_u32 s7, s7, 0
	s_add_u32 s27, s8, 0x100
	s_addc_u32 s53, s9, 0
	s_mov_b32 s54, -2
	v_mov_b64_e32 v[0:1], 0
	v_mov_b64_e32 v[2:3], 0
	v_mov_b64_e32 v[4:5], 0
	v_mov_b64_e32 v[6:7], 0
	v_mov_b64_e32 v[8:9], 0
	v_mov_b64_e32 v[10:11], 0
	v_mov_b64_e32 v[12:13], 0
	v_mov_b64_e32 v[14:15], 0
	v_mov_b64_e32 v[16:17], 0
	v_mov_b64_e32 v[18:19], 0
	v_mov_b64_e32 v[20:21], 0
	v_mov_b64_e32 v[22:23], 0
	v_mov_b64_e32 v[24:25], 0
	v_mov_b64_e32 v[26:27], 0
	v_mov_b64_e32 v[28:29], 0
	v_mov_b64_e32 v[30:31], 0
	v_mov_b64_e32 v[32:33], 0
	v_mov_b64_e32 v[34:35], 0
	v_mov_b64_e32 v[36:37], 0
	v_mov_b64_e32 v[38:39], 0
	v_mov_b64_e32 v[40:41], 0
	v_mov_b64_e32 v[42:43], 0
	v_mov_b64_e32 v[44:45], 0
	v_mov_b64_e32 v[46:47], 0
	v_mov_b64_e32 v[48:49], 0
	v_mov_b64_e32 v[50:51], 0
	v_mov_b64_e32 v[52:53], 0
	v_mov_b64_e32 v[54:55], 0
	v_mov_b64_e32 v[56:57], 0
	v_mov_b64_e32 v[58:59], 0
	v_mov_b64_e32 v[60:61], 0
	v_mov_b64_e32 v[62:63], 0
	v_mov_b64_e32 v[64:65], 0
	v_mov_b64_e32 v[66:67], 0
	v_mov_b64_e32 v[68:69], 0
	v_mov_b64_e32 v[70:71], 0
	v_mov_b64_e32 v[72:73], 0
	v_mov_b64_e32 v[74:75], 0
	v_mov_b64_e32 v[76:77], 0
	v_mov_b64_e32 v[78:79], 0
	v_mov_b64_e32 v[80:81], 0
	v_mov_b64_e32 v[82:83], 0
	v_mov_b64_e32 v[84:85], 0
	v_mov_b64_e32 v[86:87], 0
	v_mov_b64_e32 v[88:89], 0
	v_mov_b64_e32 v[90:91], 0
	v_mov_b64_e32 v[92:93], 0
	v_mov_b64_e32 v[94:95], 0
	v_mov_b64_e32 v[96:97], 0
	v_mov_b64_e32 v[98:99], 0
	v_mov_b64_e32 v[100:101], 0
	v_mov_b64_e32 v[102:103], 0
	v_mov_b64_e32 v[104:105], 0
	v_mov_b64_e32 v[106:107], 0
	v_mov_b64_e32 v[108:109], 0
	v_mov_b64_e32 v[110:111], 0
	v_mov_b64_e32 v[112:113], 0
	v_mov_b64_e32 v[114:115], 0
	v_mov_b64_e32 v[116:117], 0
	v_mov_b64_e32 v[118:119], 0
	v_mov_b64_e32 v[120:121], 0
	v_mov_b64_e32 v[122:123], 0
	v_mov_b64_e32 v[124:125], 0
	v_mov_b64_e32 v[126:127], 0

.LBB0_979:
	s_ashr_i32 s15, s14, 31
	s_lshl_b64 s[16:17], s[14:15], 19
	s_add_u32 s16, s25, s16
	s_addc_u32 s17, s26, s17
	s_and_b64 s[18:19], s[0:1], exec
	s_cselect_b32 s15, s17, s23
	s_cselect_b32 s51, s16, s22
	s_ashr_i32 s13, s12, 31
	s_lshl_b64 s[18:19], s[12:13], 19
	s_add_u32 s18, s27, s18
	s_addc_u32 s19, s33, s19
	s_and_b64 s[36:37], s[0:1], exec
	s_cselect_b32 s13, s19, s35
	s_cselect_b32 s52, s18, s34
	s_add_u32 s22, s22, 0x40080
	s_addc_u32 s23, s23, 0
	s_add_u32 s53, s34, 0x100
	s_addc_u32 s54, s35, 0
	s_mov_b32 s55, -2
	s_waitcnt lgkmcnt(0)
	v_mov_b64_e32 v[0:1], 0
	v_mov_b64_e32 v[2:3], 0
	v_mov_b64_e32 v[4:5], 0
	v_mov_b64_e32 v[6:7], 0
	v_mov_b64_e32 v[8:9], 0
	v_mov_b64_e32 v[10:11], 0
	v_mov_b64_e32 v[12:13], 0
	v_mov_b64_e32 v[14:15], 0
	v_mov_b64_e32 v[16:17], 0
	v_mov_b64_e32 v[18:19], 0
	v_mov_b64_e32 v[20:21], 0
	v_mov_b64_e32 v[22:23], 0
	v_mov_b64_e32 v[24:25], 0
	v_mov_b64_e32 v[26:27], 0
	v_mov_b64_e32 v[28:29], 0
	v_mov_b64_e32 v[30:31], 0
	v_mov_b64_e32 v[32:33], 0
	v_mov_b64_e32 v[34:35], 0
	v_mov_b64_e32 v[36:37], 0
	v_mov_b64_e32 v[38:39], 0
	v_mov_b64_e32 v[40:41], 0
	v_mov_b64_e32 v[42:43], 0
	v_mov_b64_e32 v[44:45], 0
	v_mov_b64_e32 v[46:47], 0
	v_mov_b64_e32 v[48:49], 0
	v_mov_b64_e32 v[50:51], 0
	v_mov_b64_e32 v[52:53], 0
	v_mov_b64_e32 v[54:55], 0
	v_mov_b64_e32 v[56:57], 0
	v_mov_b64_e32 v[58:59], 0
	v_mov_b64_e32 v[60:61], 0
	v_mov_b64_e32 v[62:63], 0
	v_mov_b64_e32 v[64:65], 0
	v_mov_b64_e32 v[66:67], 0
	v_mov_b64_e32 v[68:69], 0
	v_mov_b64_e32 v[70:71], 0
	v_mov_b64_e32 v[72:73], 0
	v_mov_b64_e32 v[74:75], 0
	v_mov_b64_e32 v[76:77], 0
	v_mov_b64_e32 v[78:79], 0
	v_mov_b64_e32 v[80:81], 0
	v_mov_b64_e32 v[82:83], 0
	v_mov_b64_e32 v[84:85], 0
	v_mov_b64_e32 v[86:87], 0
	v_mov_b64_e32 v[88:89], 0
	v_mov_b64_e32 v[90:91], 0
	v_mov_b64_e32 v[92:93], 0
	v_mov_b64_e32 v[94:95], 0
	v_mov_b64_e32 v[96:97], 0
	v_mov_b64_e32 v[98:99], 0
	v_mov_b64_e32 v[100:101], 0
	v_mov_b64_e32 v[102:103], 0
	v_mov_b64_e32 v[104:105], 0
	v_mov_b64_e32 v[106:107], 0
	v_mov_b64_e32 v[108:109], 0
	v_mov_b64_e32 v[110:111], 0
	v_mov_b64_e32 v[112:113], 0
	v_mov_b64_e32 v[114:115], 0
	v_mov_b64_e32 v[116:117], 0
	v_mov_b64_e32 v[118:119], 0
	v_mov_b64_e32 v[120:121], 0
	v_mov_b64_e32 v[122:123], 0
	v_mov_b64_e32 v[124:125], 0
	v_mov_b64_e32 v[126:127], 0

.LBB0_1060:
	s_add_u32 s4, s36, 0xb0080
	s_addc_u32 s5, s37, 0
	s_add_u32 s23, s34, 0x100
	s_addc_u32 s27, s35, 0
	s_mov_b32 s58, -2
	s_waitcnt lgkmcnt(0)
	v_mov_b64_e32 v[0:1], 0
	v_mov_b64_e32 v[2:3], 0
	v_mov_b64_e32 v[4:5], 0
	v_mov_b64_e32 v[6:7], 0
	v_mov_b64_e32 v[8:9], 0
	v_mov_b64_e32 v[10:11], 0
	v_mov_b64_e32 v[12:13], 0
	v_mov_b64_e32 v[14:15], 0
	v_mov_b64_e32 v[16:17], 0
	v_mov_b64_e32 v[18:19], 0
	v_mov_b64_e32 v[20:21], 0
	v_mov_b64_e32 v[22:23], 0
	v_mov_b64_e32 v[24:25], 0
	v_mov_b64_e32 v[26:27], 0
	v_mov_b64_e32 v[28:29], 0
	v_mov_b64_e32 v[30:31], 0
	v_mov_b64_e32 v[32:33], 0
	v_mov_b64_e32 v[34:35], 0
	v_mov_b64_e32 v[36:37], 0
	v_mov_b64_e32 v[38:39], 0
	v_mov_b64_e32 v[40:41], 0
	v_mov_b64_e32 v[42:43], 0
	v_mov_b64_e32 v[44:45], 0
	v_mov_b64_e32 v[46:47], 0
	v_mov_b64_e32 v[48:49], 0
	v_mov_b64_e32 v[50:51], 0
	v_mov_b64_e32 v[52:53], 0
	v_mov_b64_e32 v[54:55], 0
	v_mov_b64_e32 v[56:57], 0
	v_mov_b64_e32 v[58:59], 0
	v_mov_b64_e32 v[60:61], 0
	v_mov_b64_e32 v[62:63], 0
	v_mov_b64_e32 v[64:65], 0
	v_mov_b64_e32 v[66:67], 0
	v_mov_b64_e32 v[68:69], 0
	v_mov_b64_e32 v[70:71], 0
	v_mov_b64_e32 v[72:73], 0
	v_mov_b64_e32 v[74:75], 0
	v_mov_b64_e32 v[76:77], 0
	v_mov_b64_e32 v[78:79], 0
	v_mov_b64_e32 v[80:81], 0
	v_mov_b64_e32 v[82:83], 0
	v_mov_b64_e32 v[84:85], 0
	v_mov_b64_e32 v[86:87], 0
	v_mov_b64_e32 v[88:89], 0
	v_mov_b64_e32 v[90:91], 0
	v_mov_b64_e32 v[92:93], 0
	v_mov_b64_e32 v[94:95], 0
	v_mov_b64_e32 v[96:97], 0
	v_mov_b64_e32 v[98:99], 0
	v_mov_b64_e32 v[100:101], 0
	v_mov_b64_e32 v[102:103], 0
	v_mov_b64_e32 v[104:105], 0
	v_mov_b64_e32 v[106:107], 0
	v_mov_b64_e32 v[108:109], 0
	v_mov_b64_e32 v[110:111], 0
	v_mov_b64_e32 v[112:113], 0
	v_mov_b64_e32 v[114:115], 0
	v_mov_b64_e32 v[116:117], 0
	v_mov_b64_e32 v[118:119], 0
	v_mov_b64_e32 v[120:121], 0
	v_mov_b64_e32 v[122:123], 0
	v_mov_b64_e32 v[124:125], 0
	v_mov_b64_e32 v[126:127], 0
